# X48: HGRN2 pass-3 unit start - counted vmcnt waits (the prefetched raw inputs, then the gate-bias words, then the entering-state fragments just before the next unit's prefetch) instead of one full wai
# speedup vs baseline: 1.0018x; 1.0018x over previous
; __device__ __forceinline__ float sigmoidf_(float v) { return __builtin_amdgcn_rcpf(1.0f + __builtin_amdgcn_exp2f(v * -1.4426950408889634f)); }
; __device__ __forceinline__ float siluf_(float v) { return v * __builtin_amdgcn_rcpf(1.0f + __builtin_amdgcn_exp2f(v * -1.4426950408889634f)); }
; __device__ __forceinline__ float hg_lb(const float* lg, int l, int ch) {
;     float mx = lg[ch];
; #pragma unroll
;     for (int i = 1; i < DEPTH; ++i) mx = fmaxf(mx, lg[i * 512 + ch]);
;     float den = 0.f, num = 0.f;
; #pragma unroll
;     for (int i = 0; i < DEPTH; ++i) { const float e = __expf(lg[i * 512 + ch] - mx); den += e; if (i >= 1 && i <= l) num += e; }
;     return num / den;
; __device__ __forceinline__ void hg_p3_unit(const Args& a, unsigned char* ws, int l, int unit, int next, HgRaw& R, LAS unsigned char* lds, int tid_in) {
;     ...
;     const float lb = hg_lb(a.in[I_LBL], l, ch);
;     const size_t rowc = (size_t)b * SEQ + (size_t)chunk * 64, row0 = rowc + 16 * qt;
;     bf16x8_t sf[4]; v2u grv[4];
;     { const size_t sbase = ((size_t)(b * 4 + h) * HG_NCH + chunk) * 16384 + (size_t)(16 * wave + fr) * 128 + 8 * g;
; #pragma unroll
;       for (int ks = 0; ks < 4; ++ks) sf[ks] = *(const bf16x8_t*)(SPT + sbase + 32 * ks);
; #pragma unroll
;       for (int j = 0; j < 4; ++j) grv[j] = *(const v2u*)(proj + (rowc + 16 * j + fr) * NPROJ + PC_AG + h * 128 + 16 * wave + 4 * g); }
;     float rr[16], kk[16], qq[16], vv[16];
;     { float ff[16];
; #pragma unroll
;       for (int i = 0; i < 16; ++i) { const float z = bf2f(R.z[i]); vv[i] = bf2f(R.v[i]); qq[i] = siluf_(bf2f(R.q[i]));
;           const float sg = sigmoidf_(z); ff[i] = lb + (1.0f - lb) * sg; kk[i] = (1.0f - lb) * (1.0f - sg); }
.LBB0_1217:
	v_mov_b32_e32 v101, v210
	s_and_b32 s3, s50, 3
	s_lshl_b32 s2, s3, 7
	v_and_b32_e32 v103, 0x7f, v101
	v_or_b32_e32 v2, s2, v103
	v_readlane_b32 s4, v252, 21
	v_lshlrev_b32_e32 v4, 2, v2
	v_readlane_b32 s5, v252, 22
	s_nop 4
	global_load_dword v36, v4, s[4:5]
	global_load_dword v46, v4, s[4:5] offset:2048
	v_lshl_add_u64 v[2:3], s[4:5], 0, v[4:5]
	s_movk_i32 s4, 0x1000
	v_add_co_u32_e32 v2, vcc, s4, v2
	v_and_b32_e32 v100, 15, v101
	s_nop 0
	v_addc_co_u32_e32 v3, vcc, 0, v3, vcc
	global_load_dword v47, v[2:3], off
	s_nop 0
	global_load_dword v2, v[2:3], off offset:2048
	v_ashrrev_i32_e32 v3, 6, v101
	v_lshlrev_b32_e32 v48, 4, v3
	v_or_b32_e32 v22, v48, v100
	v_ashrrev_i32_e32 v23, 31, v22
	v_lshlrev_b64 v[12:13], 8, v[22:23]
	v_readlane_b32 s6, v252, 23
	s_ashr_i32 s22, s50, 10
	s_lshl_b32 s6, s22, 2
	s_bfe_u32 s4, s50, 0x80002
	s_ashr_i32 s23, s22, 31
	s_or_b32 s34, s6, s3
	s_lshl_b32 s5, s4, 6
	s_lshl_b64 s[22:23], s[22:23], 14
	s_ashr_i32 s35, s34, 31
	s_or_b32 s5, s22, s5
	s_lshl_b64 s[34:35], s[34:35], 23
	v_readlane_b32 s7, v252, 24
	s_add_u32 s6, s46, s34
	s_addc_u32 s7, s47, s35
	s_lshl_b32 s4, s4, 15
	v_mov_b64_e32 v[34:35], s[0:1]
	v_or_b32_e32 v44, s5, v100
	s_add_u32 s34, s6, s4
	v_mad_u64_u32 v[8:9], s[40:41], v44, s73, v[34:35]
	s_addc_u32 s35, s7, 0
	v_ashrrev_i32_e32 v49, 31, v48
	v_mad_i32_i24 v9, s23, v203, v9
	s_lshl_b32 s24, s3, 8
	v_lshl_add_u64 v[12:13], s[34:35], 0, v[12:13]
	v_bfe_u32 v132, v101, 4, 2
	v_lshlrev_b64 v[38:39], 1, v[48:49]
	v_lshl_add_u64 v[8:9], v[8:9], 0, s[24:25]
	v_lshlrev_b32_e32 v4, 3, v132
	v_lshl_add_u64 v[24:25], v[8:9], 0, v[38:39]
	v_lshl_add_u64 v[24:25], v[24:25], 0, v[4:5]
	s_mov_b32 s3, 0x12a00000
	v_or_b32_e32 v99, 16, v100
	v_or_b32_e32 v40, s5, v99
	v_mad_u64_u32 v[10:11], s[40:41], v40, s73, v[34:35]
	v_or_b32_e32 v87, 32, v100
	v_mad_i32_i24 v11, s23, v203, v11
	v_lshl_add_u64 v[10:11], v[10:11], 0, s[24:25]
	v_lshl_add_u64 v[42:43], v[10:11], 0, v[38:39]
	v_lshl_add_u64 v[42:43], v[42:43], 0, v[4:5]
	v_mov_b32_e32 v7, v5
	v_and_b32_e32 v6, 48, v101
	v_lshl_add_u64 v[6:7], v[12:13], 0, v[6:7]
	global_load_dwordx4 v[18:21], v[6:7], off
	global_load_dwordx4 v[14:17], v[6:7], off offset:64
	global_load_dwordx4 v[10:13], v[6:7], off offset:128
	s_nop 0
	global_load_dwordx4 v[6:9], v[6:7], off offset:192
	s_waitcnt vmcnt(8)
	v_lshlrev_b32_e32 v68, 16, v51
	v_mul_f32_e32 v68, 0xbfb8aa3b, v68
	v_exp_f32_e32 v68, v68
	v_lshlrev_b32_e32 v70, 16, v1
	v_mul_f32_e32 v70, 0xbfb8aa3b, v70
	v_lshlrev_b32_e32 v71, 16, v60
	v_exp_f32_e32 v70, v70
	v_mul_f32_e32 v71, 0xbfb8aa3b, v71
	v_exp_f32_e32 v71, v71
	v_lshlrev_b32_e32 v73, 16, v59
	v_mul_f32_e32 v73, 0xbfb8aa3b, v73
	v_lshlrev_b32_e32 v74, 16, v57
	v_exp_f32_e32 v73, v73
	v_mul_f32_e32 v74, 0xbfb8aa3b, v74
	v_exp_f32_e32 v74, v74
	v_lshlrev_b32_e32 v78, 16, v64
	v_mul_f32_e32 v78, 0xbfb8aa3b, v78
	v_exp_f32_e32 v78, v78
	v_mov_b32_e32 v45, s23
	v_readlane_b32 s8, v252, 25
	s_waitcnt vmcnt(4)
; __device__ __forceinline__ float sigmoidf_(float v) { return __builtin_amdgcn_rcpf(1.0f + __builtin_amdgcn_exp2f(v * -1.4426950408889634f)); }
; __device__ __forceinline__ float siluf_(float v) { return v * __builtin_amdgcn_rcpf(1.0f + __builtin_amdgcn_exp2f(v * -1.4426950408889634f)); }
; __device__ __forceinline__ float hg_lb(const float* lg, int l, int ch) {
;     float mx = lg[ch];
; #pragma unroll
;     for (int i = 1; i < DEPTH; ++i) mx = fmaxf(mx, lg[i * 512 + ch]);
;     float den = 0.f, num = 0.f;
; #pragma unroll
;     for (int i = 0; i < DEPTH; ++i) { const float e = __expf(lg[i * 512 + ch] - mx); den += e; if (i >= 1 && i <= l) num += e; }
;     return num / den;
; __device__ __forceinline__ void hg_p3_unit(const Args& a, unsigned char* ws, int l, int unit, int next, HgRaw& R, LAS unsigned char* lds, int tid_in) {
;     ...
;       for (int j = 0; j < 4; ++j) grv[j] = *(const v2u*)(proj + (rowc + 16 * j + fr) * NPROJ + PC_AG + h * 128 + 16 * wave + 4 * g); }
;     float rr[16], kk[16], qq[16], vv[16];
;     { float ff[16];
; #pragma unroll
;       for (int i = 0; i < 16; ++i) { const float z = bf2f(R.z[i]); vv[i] = bf2f(R.v[i]); qq[i] = siluf_(bf2f(R.q[i]));
;           const float sg = sigmoidf_(z); ff[i] = lb + (1.0f - lb) * sg; kk[i] = (1.0f - lb) * (1.0f - sg); }
;       float run = 1.0f;
;       if (qt < 2) {
; #pragma unroll
;           for (int i = 15; i >= 0; --i) { rr[i] = run; run *= ff[i]; }
;       } else {
; #pragma unroll
;           for (int i = 0; i < 16; ++i) { run *= ff[i]; rr[i] = run; } }
	v_max_f32_e32 v65, v36, v36
	v_max_f32_e32 v23, v46, v46
	v_max_f32_e32 v23, v65, v23
	v_readlane_b32 s9, v252, 26
	v_readlane_b32 s10, v252, 27
	v_readlane_b32 s11, v252, 28
	v_readlane_b32 s12, v252, 29
	v_readlane_b32 s13, v252, 30
	v_readlane_b32 s14, v252, 31
	v_max3_f32 v23, v23, v47, v2
	v_sub_f32_e32 v36, v36, v23
	v_sub_f32_e32 v46, v46, v23
	v_sub_f32_e32 v47, v47, v23
	v_sub_f32_e32 v2, v2, v23
	v_mul_f32_e32 v23, 0x3fb8aa3b, v36
	v_mul_f32_e32 v36, 0x3fb8aa3b, v46
	v_exp_f32_e32 v36, v36
	v_mul_f32_e32 v46, 0x3fb8aa3b, v47
	v_exp_f32_e32 v23, v23
	v_exp_f32_e32 v46, v46
	v_mul_f32_e32 v2, 0x3fb8aa3b, v2
	v_exp_f32_e32 v2, v2
	v_add_f32_e32 v47, 0, v36
	v_add_f32_e32 v23, 0, v23
	v_cndmask_b32_e64 v47, v47, 0, s[42:43]
	v_add_f32_e32 v23, v36, v23
	v_add_f32_e32 v36, v46, v47
	v_add_f32_e32 v23, v46, v23
	v_cndmask_b32_e64 v36, v36, v47, s[36:37]
	v_add_f32_e32 v23, v2, v23
	v_add_f32_e32 v2, v2, v36
	v_cndmask_b32_e64 v2, v2, v36, s[38:39]
	v_div_scale_f32 v36, s[34:35], v23, v23, v2
	v_rcp_f32_e32 v65, v36
	v_add_co_u32_e32 v46, vcc, s3, v24
	v_readlane_b32 s15, v252, 32
	s_nop 0
	v_addc_co_u32_e32 v47, vcc, 0, v25, vcc
	v_fma_f32 v25, -v36, v65, 1.0
	v_div_scale_f32 v24, vcc, v2, v23, v2
	v_fmac_f32_e32 v65, v25, v65
	v_mul_f32_e32 v25, v24, v65
	v_fma_f32 v66, -v36, v25, v24
	v_fmac_f32_e32 v25, v66, v65
	v_fma_f32 v24, -v36, v25, v24
	v_or_b32_e32 v36, s5, v87
	v_div_fmas_f32 v24, v24, v65, v25
	v_mad_u64_u32 v[66:67], s[34:35], v36, s73, v[34:35]
	v_or_b32_e32 v65, 48, v100
	v_div_fixup_f32 v24, v24, v23, v2
	v_mad_i32_i24 v67, s23, v203, v67
	v_or_b32_e32 v2, s5, v65
	v_lshl_add_u64 v[66:67], v[66:67], 0, s[24:25]
	v_mad_u64_u32 v[34:35], s[34:35], v2, s73, v[34:35]
	v_add_co_u32_e32 v42, vcc, s3, v42
	v_lshl_add_u64 v[66:67], v[66:67], 0, v[38:39]
	v_mad_i32_i24 v35, s23, v203, v35
	v_addc_co_u32_e32 v43, vcc, 0, v43, vcc
	v_lshl_add_u64 v[66:67], v[66:67], 0, v[4:5]
	v_lshl_add_u64 v[34:35], v[34:35], 0, s[24:25]
	v_add_co_u32_e32 v66, vcc, s3, v66
	v_lshl_add_u64 v[34:35], v[34:35], 0, v[38:39]
	s_nop 0
	v_addc_co_u32_e32 v67, vcc, 0, v67, vcc
	v_lshl_add_u64 v[34:35], v[34:35], 0, v[4:5]
	v_add_co_u32_e32 v34, vcc, s3, v34
	v_lshlrev_b32_e32 v23, 16, v52
	s_nop 0
	v_addc_co_u32_e32 v35, vcc, 0, v35, vcc
	global_load_dwordx2 v[46:47], v[46:47], off offset:3072
	s_nop 0
	global_load_dwordx2 v[42:43], v[42:43], off offset:3072
	s_nop 0
	global_load_dwordx2 v[38:39], v[66:67], off offset:3072
	s_nop 0
	global_load_dwordx2 v[34:35], v[34:35], off offset:3072
	v_mul_f32_e32 v23, 0xbfb8aa3b, v23
	v_exp_f32_e32 v25, v23
	v_lshlrev_b32_e32 v23, 16, v62
	v_mul_f32_e32 v23, 0xbfb8aa3b, v23
	v_exp_f32_e32 v66, v23
	v_add_f32_e32 v25, 1.0, v25
	v_rcp_f32_e32 v163, v25
	v_lshlrev_b32_e32 v67, 16, v55
	v_add_f32_e32 v25, 1.0, v66
	v_rcp_f32_e32 v157, v25
	v_lshlrev_b32_e32 v25, 16, v56
	v_mul_f32_e32 v25, 0xbfb8aa3b, v25
	v_exp_f32_e32 v66, v25
	v_mul_f32_e32 v67, 0xbfb8aa3b, v67
	v_exp_f32_e32 v67, v67
	v_ashrrev_i32_e32 v23, 7, v101
	v_add_f32_e32 v66, 1.0, v66
	v_rcp_f32_e32 v158, v66
	v_add_f32_e32 v66, 1.0, v67
	v_rcp_f32_e32 v156, v66
	v_add_f32_e32 v66, 1.0, v68
	v_rcp_f32_e32 v154, v66
	v_lshlrev_b32_e32 v66, 16, v58
	v_mul_f32_e32 v66, 0xbfb8aa3b, v66
	v_exp_f32_e32 v69, v66
	v_sub_f32_e32 v135, 1.0, v24
	v_fma_f32 v136, v163, v135, v24
	v_fma_f32 v25, v157, v135, v24
	v_add_f32_e32 v69, 1.0, v69
	v_rcp_f32_e32 v155, v69
	v_add_f32_e32 v69, 1.0, v70
	v_rcp_f32_e32 v153, v69
	v_add_f32_e32 v69, 1.0, v71
	v_rcp_f32_e32 v151, v69
	v_lshlrev_b32_e32 v69, 16, v63
	v_mul_f32_e32 v69, 0xbfb8aa3b, v69
	v_exp_f32_e32 v72, v69
	v_fma_f32 v66, v158, v135, v24
	v_fma_f32 v67, v156, v135, v24
	v_fma_f32 v68, v154, v135, v24
	v_add_f32_e32 v72, 1.0, v72
	v_rcp_f32_e32 v152, v72
	v_add_f32_e32 v72, 1.0, v73
	v_rcp_f32_e32 v150, v72
	v_add_f32_e32 v72, 1.0, v74
	v_rcp_f32_e32 v149, v72
	v_lshlrev_b32_e32 v72, 16, v54
	v_mul_f32_e32 v72, 0xbfb8aa3b, v72
	v_exp_f32_e32 v75, v72
	v_fma_f32 v69, v155, v135, v24
	v_fma_f32 v70, v153, v135, v24
	v_fma_f32 v71, v151, v135, v24
	v_add_f32_e32 v75, 1.0, v75
	v_rcp_f32_e32 v147, v75
	v_lshlrev_b32_e32 v75, 16, v53
	v_mul_f32_e32 v75, 0xbfb8aa3b, v75
	v_exp_f32_e32 v76, v75
	v_lshlrev_b32_e32 v75, 16, v61
	v_mul_f32_e32 v75, 0xbfb8aa3b, v75
	v_exp_f32_e32 v77, v75
	v_add_f32_e32 v76, 1.0, v76
	v_rcp_f32_e32 v148, v76
	v_fma_f32 v72, v152, v135, v24
	v_add_f32_e32 v76, 1.0, v77
	v_lshlrev_b32_e32 v77, 16, v50
	v_mul_f32_e32 v77, 0xbfb8aa3b, v77
	v_exp_f32_e32 v77, v77
	v_rcp_f32_e32 v145, v76
	v_fma_f32 v73, v150, v135, v24
	v_fma_f32 v74, v149, v135, v24
	v_add_f32_e32 v76, 1.0, v77
	v_rcp_f32_e32 v144, v76
	v_add_f32_e32 v76, 1.0, v78
	v_rcp_f32_e32 v143, v76
	v_fma_f32 v75, v147, v135, v24
	v_fma_f32 v76, v148, v135, v24
	v_fma_f32 v77, v145, v135, v24
	v_fma_f32 v78, v144, v135, v24
	v_fmac_f32_e32 v24, v143, v135
	v_cmp_gt_i32_e64 s[40:41], 2, v23
	v_cmp_lt_i32_e32 vcc, 1, v23
	v_readlane_b32 s16, v252, 33
	v_readlane_b32 s17, v252, 34
	v_readlane_b32 s18, v252, 35
	v_readlane_b32 s19, v252, 36
	s_and_saveexec_b64 s[22:23], vcc
	s_xor_b64 s[22:23], exec, s[22:23]
	s_cbranch_execz .LBB0_1219
	v_mul_f32_e32 v146, v136, v25
	v_mul_f32_e32 v142, v66, v146
	v_mul_f32_e32 v141, v67, v142
	v_mul_f32_e32 v140, v68, v141
	v_mul_f32_e32 v139, v69, v140
	v_mul_f32_e32 v138, v70, v139
	v_mul_f32_e32 v137, v71, v138
	v_mul_f32_e32 v134, v72, v137
	v_mul_f32_e32 v133, v73, v134
	v_mul_f32_e32 v131, v74, v133
	v_mul_f32_e32 v130, v75, v131
	v_mul_f32_e32 v129, v76, v130
	v_mul_f32_e32 v127, v77, v129
	v_mul_f32_e32 v128, v78, v127
	v_mul_f32_e32 v126, v24, v128

; template <bool WITHQ> __device__ __forceinline__ void hg_load(HgRaw& R, unsigned char* ws, int unit, int tid) {
;     const bf16* proj = (const bf16*)(ws + WS_HP);
;     const int h = unit & 3, chunk = (unit >> 2) & (HG_NCH - 1), b = unit >> 10, qt = tid >> 7, col = tid & 127, ch = h * 128 + col;
;     const size_t row0 = (size_t)b * SEQ + (size_t)chunk * 64 + 16 * qt;
; #pragma unroll
;     for (int i = 0; i < 16; ++i) { const bf16* p = proj + (row0 + i) * NPROJ + ch; R.z[i] = p[PC_AF]; R.v[i] = p[PC_AI]; if (WITHQ) R.q[i] = p[PC_AQ]; }
; }
; __device__ __forceinline__ void hg_p3_unit(const Args& a, unsigned char* ws, int l, int unit, int next, HgRaw& R, LAS unsigned char* lds, int tid_in) {
;     ...
;       tots[qt * 128 + col] = run; }
;     if (next >= 0) hg_load<true>(R, ws, next, tid);
.LBB0_1221:
	s_or_b64 exec, exec, s[22:23]
	s_add_i32 s50, s50, s62
	s_cmpk_gt_i32 s50, 0x7ff
	s_cselect_b64 s[44:45], -1, 0
	s_cmpk_lt_i32 s50, 0x800
	v_lshl_add_u32 v24, v101, 2, 0
	s_cselect_b32 s3, s50, -1
	v_add_u32_e32 v24, 0x13800, v24
	ds_write_b32 v24, v79
	s_cmp_lt_i32 s3, 0
	v_mov_b32_e32 v97, v27
	v_mov_b32_e32 v95, v29
	v_mov_b32_e32 v92, v32
	v_mov_b32_e32 v90, v33
	v_mov_b32_e32 v89, v41
	v_mov_b32_e32 v84, v105
	v_mov_b32_e32 v83, v106
	v_mov_b32_e32 v81, v108
	v_mov_b32_e32 v80, v110
	v_mov_b32_e32 v78, v112
	v_mov_b32_e32 v74, v115
	v_mov_b32_e32 v73, v116
	v_mov_b32_e32 v72, v118
	v_mov_b32_e32 v68, v120
	v_mov_b32_e32 v67, v124
	v_mov_b32_e32 v66, v122
	v_mov_b32_e32 v98, v26
	v_mov_b32_e32 v96, v28
	v_mov_b32_e32 v94, v30
	v_mov_b32_e32 v93, v31
	v_mov_b32_e32 v91, v37
	v_mov_b32_e32 v88, v102
	v_mov_b32_e32 v86, v104
	v_mov_b32_e32 v85, v107
	v_mov_b32_e32 v82, v109
	v_mov_b32_e32 v79, v111
	v_mov_b32_e32 v77, v113
	v_mov_b32_e32 v76, v114
	v_mov_b32_e32 v75, v117
	v_mov_b32_e32 v71, v119
	v_mov_b32_e32 v70, v121
	v_mov_b32_e32 v69, v123
	s_waitcnt vmcnt(4)
	s_cbranch_scc1 .LBB0_1223
	s_lshr_b32 s24, s3, 10
	s_lshl_b32 s4, s3, 7
	s_lshl_b32 s3, s3, 4
	v_ashrrev_i32_e32 v24, 3, v101
	s_and_b32 s4, s4, 0x180
	s_lshl_b64 s[22:23], s[24:25], 14
	s_and_b32 s3, s3, 0x3fc0
	v_and_b32_e32 v24, -16, v24
	v_or_b32_e32 v1, s4, v103
	s_or_b32 s22, s22, s3
	v_ashrrev_i32_e32 v25, 31, v24
	v_lshl_add_u64 v[50:51], s[22:23], 0, v[24:25]
	v_lshlrev_b32_e32 v24, 1, v1
	v_mov_b32_e32 v25, v5
	v_lshl_add_u64 v[24:25], s[26:27], 0, v[24:25]
	v_mad_u64_u32 v[24:25], s[22:23], v50, s73, v[24:25]
	v_mad_i32_i24 v25, v51, s73, v25
	v_add_co_u32_e32 v50, vcc, s73, v24
	global_load_ushort v52, v[24:25], off offset:1024
	global_load_ushort v69, v[24:25], off offset:2048
	global_load_ushort v66, v[24:25], off
	v_addc_co_u32_e32 v51, vcc, 0, v25, vcc
	global_load_ushort v62, v[50:51], off offset:1024
	global_load_ushort v70, v[50:51], off offset:2048
	global_load_ushort v67, v[50:51], off
	v_add_co_u32_e32 v50, vcc, s77, v24
	s_mov_b32 s3, 0x9000
	s_nop 0
	v_addc_co_u32_e32 v51, vcc, 0, v25, vcc
	global_load_ushort v56, v[50:51], off offset:1024
	global_load_ushort v71, v[50:51], off offset:2048
	global_load_ushort v68, v[50:51], off
	v_add_co_u32_e32 v50, vcc, s3, v24
	s_mov_b32 s3, 0xc000
	s_nop 0
	v_addc_co_u32_e32 v51, vcc, 0, v25, vcc
	v_add_co_u32_e32 v58, vcc, s3, v24
	s_mov_b32 s3, 0xf000
	s_nop 0
	v_addc_co_u32_e32 v59, vcc, 0, v25, vcc
	v_add_co_u32_e32 v60, vcc, s3, v24
	s_mov_b32 s3, 0x12000
	s_nop 0
	v_addc_co_u32_e32 v61, vcc, 0, v25, vcc
	global_load_ushort v55, v[50:51], off offset:1024
	global_load_ushort v75, v[50:51], off offset:2048
	global_load_ushort v72, v[50:51], off
	s_nop 0
	global_load_ushort v51, v[58:59], off offset:1024
	global_load_ushort v76, v[58:59], off offset:2048
	global_load_ushort v73, v[58:59], off
	s_nop 0
	global_load_ushort v58, v[60:61], off offset:1024
	global_load_ushort v77, v[60:61], off offset:2048
	global_load_ushort v74, v[60:61], off
	v_add_co_u32_e32 v60, vcc, s3, v24
	s_mov_b32 s3, 0x15000
	s_nop 0
	v_addc_co_u32_e32 v61, vcc, 0, v25, vcc
	v_add_co_u32_e32 v80, vcc, s3, v24
	s_mov_b32 s3, 0x18000
	s_nop 0
	v_addc_co_u32_e32 v81, vcc, 0, v25, vcc
	v_add_co_u32_e32 v88, vcc, s3, v24
	s_mov_b32 s3, 0x1b000
	s_nop 0
	v_addc_co_u32_e32 v89, vcc, 0, v25, vcc
	global_load_ushort v1, v[60:61], off offset:1024
	global_load_ushort v79, v[60:61], off offset:2048
	global_load_ushort v78, v[60:61], off
	s_nop 0
	global_load_ushort v60, v[80:81], off offset:1024
	global_load_ushort v82, v[80:81], off offset:2048
	s_nop 0
	global_load_ushort v80, v[80:81], off
	s_nop 0
	global_load_ushort v63, v[88:89], off offset:1024
	global_load_ushort v85, v[88:89], off offset:2048
	global_load_ushort v81, v[88:89], off
	v_add_co_u32_e32 v88, vcc, s3, v24
	s_mov_b32 s3, 0x1e000
	s_nop 0
	v_addc_co_u32_e32 v89, vcc, 0, v25, vcc
	v_add_co_u32_e32 v90, vcc, s3, v24
	s_mov_b32 s3, 0x21000
	s_nop 0
	v_addc_co_u32_e32 v91, vcc, 0, v25, vcc
	v_add_co_u32_e32 v92, vcc, s3, v24
	s_mov_b32 s3, 0x24000
	s_nop 0
	v_addc_co_u32_e32 v93, vcc, 0, v25, vcc
	v_add_co_u32_e32 v94, vcc, s3, v24
	s_mov_b32 s3, 0x27000
	s_nop 0
	v_addc_co_u32_e32 v95, vcc, 0, v25, vcc
	v_add_co_u32_e32 v96, vcc, s3, v24
	global_load_ushort v59, v[88:89], off offset:1024
	global_load_ushort v86, v[88:89], off offset:2048
	global_load_ushort v83, v[88:89], off
	v_addc_co_u32_e32 v97, vcc, 0, v25, vcc
	v_add_co_u32_e32 v168, vcc, 0x2a000, v24
	global_load_ushort v57, v[90:91], off offset:1024
	global_load_ushort v88, v[90:91], off offset:2048
	global_load_ushort v84, v[90:91], off
	v_addc_co_u32_e32 v169, vcc, 0, v25, vcc
	v_add_co_u32_e32 v24, vcc, 0x2d000, v24
	global_load_ushort v54, v[92:93], off offset:1024
	global_load_ushort v91, v[92:93], off offset:2048
	global_load_ushort v89, v[92:93], off
	v_addc_co_u32_e32 v25, vcc, 0, v25, vcc
	global_load_ushort v53, v[94:95], off offset:1024
	global_load_ushort v93, v[94:95], off offset:2048
	global_load_ushort v90, v[94:95], off
	global_load_ushort v61, v[96:97], off offset:1024
	s_nop 0
	global_load_ushort v94, v[96:97], off offset:2048
	global_load_ushort v92, v[96:97], off
	global_load_ushort v50, v[168:169], off offset:1024
	s_nop 0
	global_load_ushort v96, v[168:169], off offset:2048
	global_load_ushort v95, v[168:169], off
	global_load_ushort v64, v[24:25], off offset:1024
	global_load_ushort v98, v[24:25], off offset:2048
	global_load_ushort v97, v[24:25], off
